# attention: waves 0..3 skip the last key tile step and the closing PV (both tiles lie wholly above their rows, P is exactly 0)
# speedup vs baseline: 1.0050x; 1.0007x over previous
; #define SBAR() __builtin_amdgcn_sched_barrier(0)
; #define RESC() do { if (resc) { asm volatile("s_waitcnt lgkmcnt(0)" ::: "memory"); \
;       _Pragma("unroll") for (int d_ = 0; d_ < 2; ++d_) _Pragma("unroll") for (int r = 0; r < 16; ++r) o[d_][r] *= wsf[crow(r, hi)]; } } while (0)
; #define PKW(P, B) pkh(P[B], P[B + 1])
; template <int THRL> __device__ __forceinline__ void attn_unit(int b, int h, int qb, const f16_t* Q, const f16_t* __restrict__ K, const f16_t* __restrict__ V, f16_t* O, const float* __restrict__ kms, char* shm) {
;     ...
;     STEP(pB0, pB1, pA0, pA1, NT - 1, false, false, false); RESC();
;     { float sacc = pB0[0] + pB0[1]; _Pragma("unroll") for (int r = 2; r < 16; ++r) sacc += pB0[r]; _Pragma("unroll") for (int r = 0; r < 16; ++r) sacc += pB1[r]; l_reg += sacc;
;       pw0 = (u32x4){PKW(pB0, 0), PKW(pB0, 2), PKW(pB0, 4), PKW(pB0, 6)}; pw1 = (u32x4){PKW(pB0, 8), PKW(pB0, 10), PKW(pB0, 12), PKW(pB0, 14)}; pw2 = (u32x4){PKW(pB1, 0), PKW(pB1, 2), PKW(pB1, 4), PKW(pB1, 6)}; pw3 = (u32x4){PKW(pB1, 8), PKW(pB1, 10), PKW(pB1, 12), PKW(pB1, 14)};
;       SBAR(); pv(o, vb0 + sl_cur, PAF(0), PAF(1), PAF(2), PAF(3)); }
;     ...
;     { auto rr = __builtin_amdgcn_permlane32_swap(__float_as_uint(l_reg), __float_as_uint(l_reg), false, false); l_reg = __uint_as_float(rr[0]) + __uint_as_float(rr[1]); }
;     if (hi == 0) wsf[32 + r32] = l_reg; asm volatile("s_waitcnt lgkmcnt(0)" ::: "memory");
.LBB0_560:
	s_cmp_gt_u32 s29, 3
	s_cbranch_scc1 .Lattn_fin_full
	v_mov_b32_e32 v51, v214
	v_lshl_add_u32 v50, v204, 4, s88
	v_cmp_gt_u32_e32 vcc, 32, v201
	v_mov_b32_e32 v34, v51
	s_nop 1
	v_permlane32_swap_b32_e32 v51, v34
	s_and_saveexec_b64 s[2:3], vcc
	s_cbranch_execz .LBB0_529
	v_add_f32_e32 v34, v51, v34
	ds_write_b32 v207, v34 offset:49280
	s_branch .LBB0_529
